# mode-5 K-loop load segments also VALU-free; modes 0,1,3,4,5 done
# baseline (speedup 1.0000x reference)
; __device__ __forceinline__ int otid() { int t = threadIdx.x; asm volatile("" : "+v"(t)); return t; }
; #define PG8_STAGE(bufoff, gbase, voff) do { _Pragma("unroll") for (int _i = 0; _i < 2; ++_i) \
;         __builtin_amdgcn_global_load_lds((const unsigned*)((const char*)(gbase) + (voff)[_i]), (LAS unsigned*)(lds + (bufoff) + ldsw + _i * 8192), 16, 0, 0); } while (0)
; #define PG8_WAIT_V(n) asm volatile("s_waitcnt vmcnt(" #n ")" ::: "memory")
; #define PG8_BAR __builtin_amdgcn_s_barrier()
; template <int MODE, class EpiT, class Sched>
; __device__ __forceinline__ void gemm_phase(LAS unsigned char* lds, const Gemm g, const Sched& S, const EpiT& E) {
;     const int tid = otid(), wid = __builtin_amdgcn_readfirstlane(tid >> 6), lane = tid & 63, wr = wid >> 2, wc = wid & 3, fr = lane & 15, fq = lane >> 4;
;     const int K = g.K, nt = K / BK;
;     unsigned voffA[2], voffB[2];
; #pragma unroll
;     for (int i = 0; i < 2; ++i) { int R, C; stage_rc(tid * 16 + i * 8192, R, C); voffA[i] = (unsigned)(R * K + C) * 2u; voffB[i] = (unsigned)(R * K + C) * 2u; }
;     const size_t kstep = (size_t)(BK * 2);
;     const size_t hstep = (size_t)HALF * K * 2;
;     const size_t tstep = 2 * hstep;
;     const unsigned ldsw = (unsigned)wid * 1024u;
;     const int aoff = lds_byte(wr * 64 + fr, fq * 8), boff = lds_byte(wc * 32 + fr, fq * 8);
;     ...
;     PG8_STAGE(PG8_SB(0, 0), cB, voffB); PG8_STAGE(PG8_SA(0, 0), cA, voffA); PG8_STAGE(PG8_SB(0, 1), cB + hstep, voffB); PG8_STAGE(PG8_SA(0, 1), cA + hstep, voffA);
;     if (wr == 1) PG8_BAR;
;     PG8_WAIT_V(4); PG8_BAR;
;     PG8_STAGE(PG8_SB(1, 0), cB + kstep, voffB); PG8_STAGE(PG8_SA(1, 0), cA + kstep, voffA); PG8_STAGE(PG8_SB(1, 1), cB + hstep + kstep, voffB);
;     PG8_WAIT_V(6); PG8_BAR;
.LBB0_106:
	s_add_i32 m0, s20, 0x18000
	v_lshl_add_u64 v[2:3], v[2:3], 0, s[76:77]
	s_waitcnt vmcnt(4)
	s_barrier
	global_load_lds_dwordx4 v[2:3], off
	v_lshl_add_u64 v[2:3], v[4:5], 0, s[76:77]
	s_add_i32 m0, s20, 0x1a000
	s_add_i32 s51, s20, 0x8000
	global_load_lds_dwordx4 v[2:3], off
	v_lshl_add_u64 v[2:3], v[6:7], 0, s[76:77]
	s_mov_b32 m0, s51
	s_add_i32 s56, s20, 0xa000
	global_load_lds_dwordx4 v[2:3], off
	v_lshl_add_u64 v[2:3], v[8:9], 0, s[76:77]
	s_mov_b32 m0, s56
	v_bfe_u32 v21, v20, 4, 2
	global_load_lds_dwordx4 v[2:3], off
	s_add_i32 m0, s20, 0x1c000
	v_lshl_add_u64 v[2:3], v[10:11], 0, s[76:77]
	global_load_lds_dwordx4 v[2:3], off
	v_lshl_add_u64 v[2:3], v[12:13], 0, s[76:77]
	s_add_i32 m0, s20, 0x1e000
	v_and_b32_e32 v22, 15, v20
	global_load_lds_dwordx4 v[2:3], off
	v_lshlrev_b32_e32 v24, 4, v21
	v_lshlrev_b32_e32 v20, 2, v20
	s_and_b32 s30, s3, 3
	v_lshl_or_b32 v181, s4, 6, v22
	v_lshl_or_b32 v22, v22, 6, v24
	s_lshl_b32 s3, s4, 13
	v_and_b32_e32 v20, 32, v20
	v_bitop3_b32 v24, v22, s3, v20 bitop3:0xde
	s_lshl_b32 s3, s30, 12
	v_bitop3_b32 v192, v22, s3, v20 bitop3:0xde
	v_add_u32_e32 v249, 0x10000, v192
	s_lshl_b32 s3, s14, 2
	v_cvt_f32_u32_e32 v2, s3
	s_lshr_b32 s50, s16, 6
	s_add_i32 s57, s50, -2
	s_ashr_i32 s61, s31, 31
	v_rcp_iflag_f32_e32 v2, v2
	s_lshl_b32 s88, s14, 3
	s_cmp_lg_u64 s[12:13], 0
	s_cselect_b64 s[68:69], -1, 0
	v_mul_f32_e32 v2, 0x4f7ffffe, v2
	v_cvt_u32_f32_e32 v2, v2
	s_sub_i32 s4, 0, s3
	v_mov_b32_e32 v3, v1
	s_waitcnt vmcnt(6)
	v_readfirstlane_b32 s5, v2
	v_add_u32_e32 v2, v16, v14
	v_add_lshl_u32 v2, v2, v15, 1
	s_mul_i32 s4, s4, s5
	v_lshl_add_u64 v[176:177], s[78:79], 0, v[2:3]
	v_add_u32_e32 v2, v19, v17
	v_lshlrev_b32_e32 v23, 3, v21
	s_mul_hi_u32 s4, s5, s4
	v_add_lshl_u32 v2, v2, v18, 1
	v_lshl_or_b32 v193, s30, 5, v23
	s_mov_b32 s60, 0
	v_cmp_eq_u32_e64 s[40:41], 0, v21
	s_mov_b32 s73, s25
	s_add_i32 s90, s5, s4
	v_lshl_add_u64 v[182:183], s[78:79], 0, v[2:3]
	v_add_u32_e32 v194, 0, v24
	s_barrier
	s_branch .LBB0_108

; #define PG8_STAGE(bufoff, gbase, voff) do { _Pragma("unroll") for (int _i = 0; _i < 2; ++_i) \
;         __builtin_amdgcn_global_load_lds((const unsigned*)((const char*)(gbase) + (voff)[_i]), (LAS unsigned*)(lds + (bufoff) + ldsw + _i * 8192), 16, 0, 0); } while (0)
; #define PG8_LDA(dst, b, h) do { _Pragma("unroll") for (int m = 0; m < 4; ++m) _Pragma("unroll") for (int k = 0; k < 2; ++k) dst[m][k] = *(const LAS bf16x8*)(lds + PG8_SA(b, h) + aoff + m * 2048 + k * 1024); } while (0)
; #define PG8_LDB(dst, b, h) do { _Pragma("unroll") for (int n = 0; n < 2; ++n) _Pragma("unroll") for (int k = 0; k < 2; ++k) dst[n][k] = *(const LAS bf16x8*)(lds + PG8_SB(b, h) + boff + n * 2048 + k * 1024); } while (0)
; #define PG8_MMA(ai, bj, At, Bt) do { __builtin_amdgcn_s_setprio(1); _Pragma("unroll") for (int m = 0; m < 4; ++m) _Pragma("unroll") for (int n = 0; n < 2; ++n) _Pragma("unroll") for (int k = 0; k < 2; ++k) \
;         acc[ai][bj][m][n] = __builtin_amdgcn_mfma_f32_16x16x32_bf16(Bt[n][k], At[m][k], acc[ai][bj][m][n], 0, 0, 0); __builtin_amdgcn_s_setprio(0); } while (0)
; #define PG8_WAIT_V(n) asm volatile("s_waitcnt vmcnt(" #n ")" ::: "memory")
; #define PG8_WAIT_L(n) asm volatile("s_waitcnt lgkmcnt(" #n ")" ::: "memory")
; #define PG8_BAR __builtin_amdgcn_s_barrier()
; #define PG8_SCHED __builtin_amdgcn_sched_barrier(0)
; template <int MODE, class EpiT, class Sched>
; __device__ __forceinline__ void gemm_phase(LAS unsigned char* lds, const Gemm g, const Sched& S, const EpiT& E) {
;     ...
;             PG8_LDB(B0, 0, 0); PG8_SCHED; PG8_LDA(At, 0, 0); PG8_STAGE(PG8_SA(1, 1), a1 + hstep, voffA);
;             PG8_WAIT_L(8); PG8_BAR; PG8_WAIT_L(0); PG8_MMA(0, 0, At, B0); PG8_BAR; PG8_SCHED;
;             PG8_LDB(B1, 0, 1); PG8_STAGE(PG8_SB(0, 0), b2, voffB);
;             PG8_BAR; PG8_WAIT_L(0); PG8_MMA(0, 1, At, B1); PG8_BAR;
;             PG8_LDA(At, 0, 1); PG8_STAGE(PG8_SA(0, 0), a2, voffA);
;             PG8_BAR; PG8_WAIT_L(0); PG8_MMA(1, 0, At, B0); PG8_BAR; PG8_SCHED;
;             PG8_STAGE(PG8_SB(0, 1), b2 + hstep, voffB);
;             PG8_WAIT_V(6); PG8_BAR; PG8_MMA(1, 1, At, B1); PG8_BAR;
.LBB0_115:
	s_add_i32 s58, s52, 2
	s_add_u32 s59, s44, 0x80
	s_addc_u32 s53, s45, 0
	s_add_u32 s100, s44, s78
	s_addc_u32 s101, s45, 0
	s_add_i32 s91, 0, 0x10000
	ds_read_b128 v[70:73], v249
	ds_read_b128 v[74:77], v249 offset:1024
	ds_read_b128 v[82:85], v249 offset:2048
	ds_read_b128 v[86:89], v249 offset:3072
	s_cmp_eq_u32 s57, s52
	s_cselect_b32 s52, s4, s59
	s_cselect_b32 s53, s5, s53
	s_cselect_b32 s75, s47, vcc_hi
	s_cselect_b32 s74, s46, vcc_lo
	s_add_i32 m0, s20, 0xc000
	ds_read_b128 v[138:141], v194
	ds_read_b128 v[142:145], v194 offset:1024
	ds_read_b128 v[146:149], v194 offset:2048
	ds_read_b128 v[154:157], v194 offset:3072
	ds_read_b128 v[162:165], v194 offset:4096
	ds_read_b128 v[166:169], v194 offset:5120
	ds_read_b128 v[170:173], v194 offset:6144
	ds_read_b128 v[184:187], v194 offset:7168
	global_load_lds_dwordx4 v0, s[100:101]
	s_add_i32 m0, s20, 0xe000
	s_nop 0
	global_load_lds_dwordx4 v174, s[100:101]
	s_waitcnt lgkmcnt(8)
	s_barrier
	s_waitcnt lgkmcnt(0)
	v_mfma_f32_16x16x32_bf16 v[158:161], v[70:73], v[138:141], v[158:161]
	v_mfma_f32_16x16x32_bf16 v[150:153], v[82:85], v[138:141], v[150:153]
	v_mfma_f32_16x16x32_bf16 v[126:129], v[70:73], v[146:149], v[126:129]
	v_mfma_f32_16x16x32_bf16 v[122:125], v[82:85], v[146:149], v[122:125]
	v_mfma_f32_16x16x32_bf16 v[110:113], v[70:73], v[162:165], v[110:113]
	v_mfma_f32_16x16x32_bf16 v[106:109], v[82:85], v[162:165], v[106:109]
	v_mfma_f32_16x16x32_bf16 v[94:97], v[70:73], v[170:173], v[94:97]
	v_mfma_f32_16x16x32_bf16 v[90:93], v[82:85], v[170:173], v[90:93]
	v_mfma_f32_16x16x32_bf16 v[158:161], v[74:77], v[142:145], v[158:161]
	v_mfma_f32_16x16x32_bf16 v[150:153], v[86:89], v[142:145], v[150:153]
	v_mfma_f32_16x16x32_bf16 v[126:129], v[74:77], v[154:157], v[126:129]
	v_mfma_f32_16x16x32_bf16 v[122:125], v[86:89], v[154:157], v[122:125]
	v_mfma_f32_16x16x32_bf16 v[110:113], v[74:77], v[166:169], v[110:113]
	v_mfma_f32_16x16x32_bf16 v[106:109], v[86:89], v[166:169], v[106:109]
	v_mfma_f32_16x16x32_bf16 v[94:97], v[74:77], v[184:187], v[94:97]
	v_mfma_f32_16x16x32_bf16 v[90:93], v[86:89], v[184:187], v[90:93]
	s_barrier
	s_add_i32 s59, 0, 0x14000
	s_add_i32 s91, s91, s9
	s_add_u32 s98, s74, 0x80
	s_addc_u32 s99, s75, 0
	s_mov_b32 m0, s91
	ds_read_b128 v[188:191], v249 offset:16384
	ds_read_b128 v[196:199], v249 offset:17408
	ds_read_b128 v[220:223], v249 offset:18432
	ds_read_b128 v[224:227], v249 offset:19456
	global_load_lds_dwordx4 v0, s[74:75]
	s_add_i32 m0, s91, 0x2000
	s_nop 0
	global_load_lds_dwordx4 v174, s[74:75]
	s_barrier
	s_waitcnt lgkmcnt(0)
	v_mfma_f32_16x16x32_bf16 v[134:137], v[188:191], v[138:141], v[134:137]
	v_mfma_f32_16x16x32_bf16 v[130:133], v[220:223], v[138:141], v[130:133]
	v_mfma_f32_16x16x32_bf16 v[118:121], v[188:191], v[146:149], v[118:121]
	v_mfma_f32_16x16x32_bf16 v[114:117], v[220:223], v[146:149], v[114:117]
	v_mfma_f32_16x16x32_bf16 v[102:105], v[188:191], v[162:165], v[102:105]
	v_mfma_f32_16x16x32_bf16 v[98:101], v[220:223], v[162:165], v[98:101]
	v_mfma_f32_16x16x32_bf16 v[78:81], v[188:191], v[170:173], v[78:81]
	v_mfma_f32_16x16x32_bf16 v[66:69], v[220:223], v[170:173], v[66:69]
	v_mfma_f32_16x16x32_bf16 v[134:137], v[196:199], v[142:145], v[134:137]
	v_mfma_f32_16x16x32_bf16 v[130:133], v[224:227], v[142:145], v[130:133]
	v_mfma_f32_16x16x32_bf16 v[118:121], v[196:199], v[154:157], v[118:121]
	v_mfma_f32_16x16x32_bf16 v[114:117], v[224:227], v[154:157], v[114:117]
	v_mfma_f32_16x16x32_bf16 v[102:105], v[196:199], v[166:169], v[102:105]
	v_mfma_f32_16x16x32_bf16 v[98:101], v[224:227], v[166:169], v[98:101]
	v_mfma_f32_16x16x32_bf16 v[78:81], v[196:199], v[184:187], v[78:81]
	v_mfma_f32_16x16x32_bf16 v[66:69], v[224:227], v[184:187], v[66:69]
	s_barrier
	s_mov_b32 m0, s20
	s_add_u32 s100, s52, 0x80
	s_addc_u32 s101, s53, 0
	ds_read_b128 v[138:141], v194 offset:16384
	ds_read_b128 v[142:145], v194 offset:17408
	ds_read_b128 v[146:149], v194 offset:18432
	ds_read_b128 v[154:157], v194 offset:19456
	ds_read_b128 v[162:165], v194 offset:20480
	ds_read_b128 v[166:169], v194 offset:21504
	ds_read_b128 v[170:173], v194 offset:22528
	ds_read_b128 v[184:187], v194 offset:23552
	global_load_lds_dwordx4 v0, s[52:53]
	s_mov_b32 m0, s21
	s_nop 0
	global_load_lds_dwordx4 v174, s[52:53]
	s_barrier
	s_waitcnt lgkmcnt(0)
	v_mfma_f32_16x16x32_bf16 v[62:65], v[70:73], v[138:141], v[62:65]
	v_mfma_f32_16x16x32_bf16 v[58:61], v[82:85], v[138:141], v[58:61]
	v_mfma_f32_16x16x32_bf16 v[46:49], v[70:73], v[146:149], v[46:49]
	v_mfma_f32_16x16x32_bf16 v[42:45], v[82:85], v[146:149], v[42:45]
	v_mfma_f32_16x16x32_bf16 v[30:33], v[70:73], v[162:165], v[30:33]
	v_mfma_f32_16x16x32_bf16 v[26:29], v[82:85], v[162:165], v[26:29]
	v_mfma_f32_16x16x32_bf16 v[14:17], v[70:73], v[170:173], v[14:17]
	v_mfma_f32_16x16x32_bf16 v[10:13], v[82:85], v[170:173], v[10:13]
	v_mfma_f32_16x16x32_bf16 v[62:65], v[74:77], v[142:145], v[62:65]
	v_mfma_f32_16x16x32_bf16 v[58:61], v[86:89], v[142:145], v[58:61]
	v_mfma_f32_16x16x32_bf16 v[46:49], v[74:77], v[154:157], v[46:49]
	v_mfma_f32_16x16x32_bf16 v[42:45], v[86:89], v[154:157], v[42:45]
	v_mfma_f32_16x16x32_bf16 v[30:33], v[74:77], v[166:169], v[30:33]
	v_mfma_f32_16x16x32_bf16 v[26:29], v[86:89], v[166:169], v[26:29]
	v_mfma_f32_16x16x32_bf16 v[14:17], v[74:77], v[184:187], v[14:17]
	v_mfma_f32_16x16x32_bf16 v[10:13], v[86:89], v[184:187], v[10:13]
	s_barrier
	s_add_u32 s74, s74, s78
	s_addc_u32 s75, s75, 0
	s_add_i32 s59, s59, s9
	s_mov_b32 m0, s59
	s_nop 0
	global_load_lds_dwordx4 v0, s[74:75]
	s_add_i32 m0, s59, 0x2000
	s_nop 0
	global_load_lds_dwordx4 v174, s[74:75]
	s_waitcnt vmcnt(6)
	s_barrier
; #define PG8_STAGE(bufoff, gbase, voff) do { _Pragma("unroll") for (int _i = 0; _i < 2; ++_i) \
;         __builtin_amdgcn_global_load_lds((const unsigned*)((const char*)(gbase) + (voff)[_i]), (LAS unsigned*)(lds + (bufoff) + ldsw + _i * 8192), 16, 0, 0); } while (0)
; #define PG8_LDA(dst, b, h) do { _Pragma("unroll") for (int m = 0; m < 4; ++m) _Pragma("unroll") for (int k = 0; k < 2; ++k) dst[m][k] = *(const LAS bf16x8*)(lds + PG8_SA(b, h) + aoff + m * 2048 + k * 1024); } while (0)
; #define PG8_LDB(dst, b, h) do { _Pragma("unroll") for (int n = 0; n < 2; ++n) _Pragma("unroll") for (int k = 0; k < 2; ++k) dst[n][k] = *(const LAS bf16x8*)(lds + PG8_SB(b, h) + boff + n * 2048 + k * 1024); } while (0)
; #define PG8_MMA(ai, bj, At, Bt) do { __builtin_amdgcn_s_setprio(1); _Pragma("unroll") for (int m = 0; m < 4; ++m) _Pragma("unroll") for (int n = 0; n < 2; ++n) _Pragma("unroll") for (int k = 0; k < 2; ++k) \
;         acc[ai][bj][m][n] = __builtin_amdgcn_mfma_f32_16x16x32_bf16(Bt[n][k], At[m][k], acc[ai][bj][m][n], 0, 0, 0); __builtin_amdgcn_s_setprio(0); } while (0)
; #define PG8_WAIT_V(n) asm volatile("s_waitcnt vmcnt(" #n ")" ::: "memory")
; #define PG8_WAIT_L(n) asm volatile("s_waitcnt lgkmcnt(" #n ")" ::: "memory")
; #define PG8_BAR __builtin_amdgcn_s_barrier()
; #define PG8_SCHED __builtin_amdgcn_sched_barrier(0)
; template <int MODE, class EpiT, class Sched>
; __device__ __forceinline__ void gemm_phase(LAS unsigned char* lds, const Gemm g, const Sched& S, const EpiT& E) {
;     ...
;             PG8_WAIT_V(6); PG8_BAR; PG8_MMA(1, 1, At, B1); PG8_BAR;
;             PG8_LDB(B0, 1, 0); PG8_SCHED; PG8_LDA(At, 1, 0); PG8_STAGE(PG8_SA(0, 1), a2 + hstep, voffA);
;             PG8_WAIT_L(8); PG8_BAR; PG8_WAIT_L(0); PG8_MMA(0, 0, At, B0); PG8_BAR; PG8_SCHED;
;             PG8_LDB(B1, 1, 1); PG8_STAGE(PG8_SB(1, 0), b3, voffB);
;             PG8_BAR; PG8_WAIT_L(0); PG8_MMA(0, 1, At, B1); PG8_BAR;
	v_mfma_f32_16x16x32_bf16 v[54:57], v[188:191], v[138:141], v[54:57]
	v_mfma_f32_16x16x32_bf16 v[50:53], v[220:223], v[138:141], v[50:53]
	v_mfma_f32_16x16x32_bf16 v[38:41], v[188:191], v[146:149], v[38:41]
	v_mfma_f32_16x16x32_bf16 v[34:37], v[220:223], v[146:149], v[34:37]
	v_mfma_f32_16x16x32_bf16 v[22:25], v[188:191], v[162:165], v[22:25]
	v_mfma_f32_16x16x32_bf16 v[18:21], v[220:223], v[162:165], v[18:21]
	v_mfma_f32_16x16x32_bf16 v[6:9], v[188:191], v[170:173], v[6:9]
	v_mfma_f32_16x16x32_bf16 v[2:5], v[220:223], v[170:173], v[2:5]
	v_mfma_f32_16x16x32_bf16 v[54:57], v[196:199], v[142:145], v[54:57]
	v_mfma_f32_16x16x32_bf16 v[50:53], v[224:227], v[142:145], v[50:53]
	v_mfma_f32_16x16x32_bf16 v[38:41], v[196:199], v[154:157], v[38:41]
	v_mfma_f32_16x16x32_bf16 v[34:37], v[224:227], v[154:157], v[34:37]
	v_mfma_f32_16x16x32_bf16 v[22:25], v[196:199], v[166:169], v[22:25]
	v_mfma_f32_16x16x32_bf16 v[18:21], v[224:227], v[166:169], v[18:21]
	v_mfma_f32_16x16x32_bf16 v[6:9], v[196:199], v[184:187], v[6:9]
	v_mfma_f32_16x16x32_bf16 v[2:5], v[224:227], v[184:187], v[2:5]
	s_barrier
	s_add_i32 s59, 0, 0x18000
	ds_read_b128 v[70:73], v249 offset:32768
	ds_read_b128 v[74:77], v249 offset:33792
	ds_read_b128 v[82:85], v249 offset:34816
	ds_read_b128 v[86:89], v249 offset:35840
	s_add_u32 s52, s52, s78
	s_addc_u32 s53, s53, 0
	s_mov_b32 m0, s22
	ds_read_b128 v[138:141], v194 offset:32768
	ds_read_b128 v[142:145], v194 offset:33792
	ds_read_b128 v[146:149], v194 offset:34816
	ds_read_b128 v[154:157], v194 offset:35840
	ds_read_b128 v[162:165], v194 offset:36864
	ds_read_b128 v[166:169], v194 offset:37888
	ds_read_b128 v[170:173], v194 offset:38912
	ds_read_b128 v[184:187], v194 offset:39936
	global_load_lds_dwordx4 v0, s[52:53]
	s_mov_b32 m0, s23
	s_nop 0
	global_load_lds_dwordx4 v174, s[52:53]
	s_waitcnt lgkmcnt(8)
	s_barrier
	s_waitcnt lgkmcnt(0)
	v_mfma_f32_16x16x32_bf16 v[158:161], v[70:73], v[138:141], v[158:161]
	v_mfma_f32_16x16x32_bf16 v[150:153], v[82:85], v[138:141], v[150:153]
	v_mfma_f32_16x16x32_bf16 v[126:129], v[70:73], v[146:149], v[126:129]
	v_mfma_f32_16x16x32_bf16 v[122:125], v[82:85], v[146:149], v[122:125]
	v_mfma_f32_16x16x32_bf16 v[110:113], v[70:73], v[162:165], v[110:113]
	v_mfma_f32_16x16x32_bf16 v[106:109], v[82:85], v[162:165], v[106:109]
	v_mfma_f32_16x16x32_bf16 v[94:97], v[70:73], v[170:173], v[94:97]
	v_mfma_f32_16x16x32_bf16 v[90:93], v[82:85], v[170:173], v[90:93]
	v_mfma_f32_16x16x32_bf16 v[158:161], v[74:77], v[142:145], v[158:161]
	v_mfma_f32_16x16x32_bf16 v[150:153], v[86:89], v[142:145], v[150:153]
	v_mfma_f32_16x16x32_bf16 v[126:129], v[74:77], v[154:157], v[126:129]
	v_mfma_f32_16x16x32_bf16 v[122:125], v[86:89], v[154:157], v[122:125]
	v_mfma_f32_16x16x32_bf16 v[110:113], v[74:77], v[166:169], v[110:113]
	v_mfma_f32_16x16x32_bf16 v[106:109], v[86:89], v[166:169], v[106:109]
	v_mfma_f32_16x16x32_bf16 v[94:97], v[74:77], v[184:187], v[94:97]
	v_mfma_f32_16x16x32_bf16 v[90:93], v[86:89], v[184:187], v[90:93]
	s_barrier
	s_add_i32 s52, 0, 0x1c000
	s_add_i32 s53, s59, s9
	s_mov_b32 m0, s53
	ds_read_b128 v[188:191], v249 offset:49152
	ds_read_b128 v[196:199], v249 offset:50176
	ds_read_b128 v[220:223], v249 offset:51200
	ds_read_b128 v[224:227], v249 offset:52224
	global_load_lds_dwordx4 v0, s[98:99]
	s_add_i32 m0, s53, 0x2000
	s_nop 0
	global_load_lds_dwordx4 v174, s[98:99]
	s_barrier
	s_waitcnt lgkmcnt(0)
	v_mfma_f32_16x16x32_bf16 v[134:137], v[188:191], v[138:141], v[134:137]
	v_mfma_f32_16x16x32_bf16 v[130:133], v[220:223], v[138:141], v[130:133]
	v_mfma_f32_16x16x32_bf16 v[118:121], v[188:191], v[146:149], v[118:121]
	v_mfma_f32_16x16x32_bf16 v[114:117], v[220:223], v[146:149], v[114:117]
	v_mfma_f32_16x16x32_bf16 v[102:105], v[188:191], v[162:165], v[102:105]
	v_mfma_f32_16x16x32_bf16 v[98:101], v[220:223], v[162:165], v[98:101]
	v_mfma_f32_16x16x32_bf16 v[78:81], v[188:191], v[170:173], v[78:81]
	v_mfma_f32_16x16x32_bf16 v[66:69], v[220:223], v[170:173], v[66:69]
	v_mfma_f32_16x16x32_bf16 v[134:137], v[196:199], v[142:145], v[134:137]
	v_mfma_f32_16x16x32_bf16 v[130:133], v[224:227], v[142:145], v[130:133]
	v_mfma_f32_16x16x32_bf16 v[118:121], v[196:199], v[154:157], v[118:121]
	v_mfma_f32_16x16x32_bf16 v[114:117], v[224:227], v[154:157], v[114:117]
	v_mfma_f32_16x16x32_bf16 v[102:105], v[196:199], v[166:169], v[102:105]
	v_mfma_f32_16x16x32_bf16 v[98:101], v[224:227], v[166:169], v[98:101]
	v_mfma_f32_16x16x32_bf16 v[78:81], v[196:199], v[184:187], v[78:81]
	v_mfma_f32_16x16x32_bf16 v[66:69], v[224:227], v[184:187], v[66:69]
	s_barrier
; #define PG8_STAGE(bufoff, gbase, voff) do { _Pragma("unroll") for (int _i = 0; _i < 2; ++_i) \
;         __builtin_amdgcn_global_load_lds((const unsigned*)((const char*)(gbase) + (voff)[_i]), (LAS unsigned*)(lds + (bufoff) + ldsw + _i * 8192), 16, 0, 0); } while (0)
; #define PG8_LDA(dst, b, h) do { _Pragma("unroll") for (int m = 0; m < 4; ++m) _Pragma("unroll") for (int k = 0; k < 2; ++k) dst[m][k] = *(const LAS bf16x8*)(lds + PG8_SA(b, h) + aoff + m * 2048 + k * 1024); } while (0)
; #define PG8_MMA(ai, bj, At, Bt) do { __builtin_amdgcn_s_setprio(1); _Pragma("unroll") for (int m = 0; m < 4; ++m) _Pragma("unroll") for (int n = 0; n < 2; ++n) _Pragma("unroll") for (int k = 0; k < 2; ++k) \
;         acc[ai][bj][m][n] = __builtin_amdgcn_mfma_f32_16x16x32_bf16(Bt[n][k], At[m][k], acc[ai][bj][m][n], 0, 0, 0); __builtin_amdgcn_s_setprio(0); } while (0)
; #define PG8_WAIT_V(n) asm volatile("s_waitcnt vmcnt(" #n ")" ::: "memory")
; #define PG8_WAIT_L(n) asm volatile("s_waitcnt lgkmcnt(" #n ")" ::: "memory")
; #define PG8_BAR __builtin_amdgcn_s_barrier()
; #define PG8_SCHED __builtin_amdgcn_sched_barrier(0)
;     template <int mode> __device__ __forceinline__ void run(const f32x4 (&acc)[2][2][4][2], const Unit& u, int wr, int wc, int fr, int fq, const LAS float* sc) const {
;     ...
;             f32x4 bvv[4];
; #pragma unroll
;             for (int q = 0; q < 4; ++q) bvv[q] = (mode != 4 && bias) ? *(const f32x4*)(bias + col0 + (q >> 1) * HALF + (q & 1) * 4) : (f32x4){0.f, 0.f, 0.f, 0.f};
; template <int MODE, class EpiT, class Sched>
; __device__ __forceinline__ void gemm_phase(LAS unsigned char* lds, const Gemm g, const Sched& S, const EpiT& E) {
;     ...
;             PG8_LDA(At, 1, 1); PG8_STAGE(PG8_SA(1, 0), a3, voffA);
;             PG8_BAR; PG8_WAIT_L(0); PG8_MMA(1, 0, At, B0); PG8_BAR; PG8_SCHED;
;             PG8_STAGE(PG8_SB(1, 1), b3 + hstep, voffB);
;             PG8_WAIT_V(6); PG8_BAR; PG8_MMA(1, 1, At, B1); PG8_BAR;
;         }
	s_mov_b32 m0, s51
	ds_read_b128 v[138:141], v194 offset:49152
	ds_read_b128 v[142:145], v194 offset:50176
	ds_read_b128 v[146:149], v194 offset:51200
	ds_read_b128 v[154:157], v194 offset:52224
	ds_read_b128 v[162:165], v194 offset:53248
	ds_read_b128 v[166:169], v194 offset:54272
	ds_read_b128 v[170:173], v194 offset:55296
	ds_read_b128 v[184:187], v194 offset:56320
	global_load_lds_dwordx4 v0, s[100:101]
	s_mov_b32 m0, s56
	s_nop 0
	global_load_lds_dwordx4 v174, s[100:101]
	s_barrier
	s_waitcnt lgkmcnt(0)
	v_mfma_f32_16x16x32_bf16 v[62:65], v[70:73], v[138:141], v[62:65]
	v_mfma_f32_16x16x32_bf16 v[58:61], v[82:85], v[138:141], v[58:61]
	v_mfma_f32_16x16x32_bf16 v[46:49], v[70:73], v[146:149], v[46:49]
	v_mfma_f32_16x16x32_bf16 v[42:45], v[82:85], v[146:149], v[42:45]
	v_mfma_f32_16x16x32_bf16 v[30:33], v[70:73], v[162:165], v[30:33]
	v_mfma_f32_16x16x32_bf16 v[26:29], v[82:85], v[162:165], v[26:29]
	v_mfma_f32_16x16x32_bf16 v[14:17], v[70:73], v[170:173], v[14:17]
	v_mfma_f32_16x16x32_bf16 v[10:13], v[82:85], v[170:173], v[10:13]
	v_mfma_f32_16x16x32_bf16 v[62:65], v[74:77], v[142:145], v[62:65]
	v_mfma_f32_16x16x32_bf16 v[58:61], v[86:89], v[142:145], v[58:61]
	v_mfma_f32_16x16x32_bf16 v[46:49], v[74:77], v[154:157], v[46:49]
	v_mfma_f32_16x16x32_bf16 v[42:45], v[86:89], v[154:157], v[42:45]
	v_mfma_f32_16x16x32_bf16 v[30:33], v[74:77], v[166:169], v[30:33]
	v_mfma_f32_16x16x32_bf16 v[26:29], v[86:89], v[166:169], v[26:29]
	v_mfma_f32_16x16x32_bf16 v[14:17], v[74:77], v[184:187], v[14:17]
	v_mfma_f32_16x16x32_bf16 v[10:13], v[86:89], v[184:187], v[10:13]
	s_barrier
	s_add_i32 s52, s52, s9
	s_add_u32 s98, s98, s78
	s_addc_u32 s99, s99, 0
	s_mov_b32 m0, s52
	s_nop 0
	global_load_lds_dwordx4 v0, s[98:99]
	s_add_i32 m0, s52, 0x2000
	s_nop 0
	global_load_lds_dwordx4 v174, s[98:99]
	s_waitcnt vmcnt(6)
	s_barrier
	v_mfma_f32_16x16x32_bf16 v[54:57], v[188:191], v[138:141], v[54:57]
	v_mfma_f32_16x16x32_bf16 v[50:53], v[220:223], v[138:141], v[50:53]
	v_mfma_f32_16x16x32_bf16 v[38:41], v[188:191], v[146:149], v[38:41]
	v_mfma_f32_16x16x32_bf16 v[34:37], v[220:223], v[146:149], v[34:37]
	v_mfma_f32_16x16x32_bf16 v[22:25], v[188:191], v[162:165], v[22:25]
	v_mfma_f32_16x16x32_bf16 v[18:21], v[220:223], v[162:165], v[18:21]
	v_mfma_f32_16x16x32_bf16 v[6:9], v[188:191], v[170:173], v[6:9]
	v_mfma_f32_16x16x32_bf16 v[2:5], v[220:223], v[170:173], v[2:5]
	v_mfma_f32_16x16x32_bf16 v[54:57], v[196:199], v[142:145], v[54:57]
	v_mfma_f32_16x16x32_bf16 v[50:53], v[224:227], v[142:145], v[50:53]
	v_mfma_f32_16x16x32_bf16 v[38:41], v[196:199], v[154:157], v[38:41]
	v_mfma_f32_16x16x32_bf16 v[34:37], v[224:227], v[154:157], v[34:37]
	v_mfma_f32_16x16x32_bf16 v[22:25], v[196:199], v[166:169], v[22:25]
	v_mfma_f32_16x16x32_bf16 v[18:21], v[224:227], v[166:169], v[18:21]
	v_mfma_f32_16x16x32_bf16 v[6:9], v[196:199], v[184:187], v[6:9]
	v_mfma_f32_16x16x32_bf16 v[2:5], v[224:227], v[184:187], v[2:5]
	s_barrier
	s_add_u32 s44, s44, 0x100
	s_addc_u32 s45, s45, 0
	s_add_u32 vcc_lo, vcc_lo, 0x100
	s_addc_u32 vcc_hi, vcc_hi, 0
	s_cmp_ge_u32 s58, s50
	s_mov_b32 s52, s58
	s_cbranch_scc0 .LBB0_115
	v_lshl_or_b32 v184, s24, 8, v193
	v_ashrrev_i32_e32 v185, 31, v184
	v_mov_b32_e32 v74, 0
	v_cndmask_b32_e64 v70, 0, 1, s[68:69]
	v_lshl_add_u64 v[138:139], v[184:185], 2, s[12:13]
	v_cmp_ne_u32_e64 s[44:45], 1, v70
	s_andn2_b64 vcc, exec, s[68:69]
	v_mov_b32_e32 v86, 0
	v_mov_b32_e32 v87, v74
	v_mov_b32_e32 v186, 0
	v_mov_b32_e32 v187, v74
	s_cbranch_vccnz .LBB0_118
	global_load_dwordx4 v[86:89], v[138:139], off
	s_waitcnt vmcnt(0)
	v_mov_b32_e32 v186, v88
	v_mov_b32_e32 v187, v89
